# M1: prologue reorder + 2-barrier k-loop with slice kt+2 DMA issued mid-iteration (vmcnt(8))
# speedup vs baseline: 1.0036x; 1.0036x over previous
.LBB0_1370:
	s_mul_hi_i32 s2, s7, 0x2aaaaaab
	s_lshr_b32 s3, s2, 31
	s_ashr_i32 s2, s2, 3
	s_add_i32 s2, s2, s3
	s_mul_i32 s3, s2, 48
	v_mov_b32_e32 v130, v155
	s_sub_i32 s8, s7, s3
	s_lshl_b32 s2, s2, 8
	s_nop 0
	v_cmp_lt_i32_e32 vcc, s39, v130
	s_barrier
	s_lshl_b32 s3, s8, 8
	v_ashrrev_i32_e32 v145, 6, v130
	v_lshrrev_b32_e32 v1, 31, v130
	v_add_u32_e32 v10, v145, v1
	v_lshrrev_b32_e32 v13, 4, v130
	v_and_b32_e32 v1, 0x1fffffe, v10
	v_xor_b32_e32 v6, v13, v130
	v_sub_u32_e32 v11, v145, v1
	v_ashrrev_i32_e32 v1, 3, v130
	v_lshlrev_b32_e32 v6, 4, v6
	v_add_u32_e32 v2, s3, v1
	v_and_b32_e32 v128, 0x70, v6
	v_add_u32_e32 v6, s2, v1
	v_ashrrev_i32_e32 v3, 31, v2
	v_ashrrev_i32_e32 v7, 31, v6
	v_lshlrev_b64 v[2:3], 11, v[2:3]
	v_lshlrev_b64 v[6:7], 11, v[6:7]
	v_lshl_add_u64 v[4:5], s[40:41], 0, v[2:3]
	v_lshl_add_u64 v[8:9], s[46:47], 0, v[6:7]
	v_lshl_add_u64 v[4:5], v[4:5], 0, v[128:129]
	v_lshl_add_u64 v[8:9], v[8:9], 0, v[128:129]
	v_lshlrev_b32_e32 v128, 4, v130
	s_nop 0
	v_readfirstlane_b32 s10, v128
	s_mov_b32 m0, s10
	s_nop 0
	global_load_lds_dwordx4 v[4:5], off
	v_add_u32_e32 v243, 0x2000, v128
	s_mov_b64 s[10:11], 0x20000
	v_lshl_add_u64 v[244:245], v[4:5], 0, s[10:11]
	v_readfirstlane_b32 s10, v243
	s_mov_b32 m0, s10
	s_nop 0
	global_load_lds_dwordx4 v[244:245], off
	v_add_u32_e32 v243, 0x4000, v128
	s_mov_b64 s[10:11], 0x40000
	v_lshl_add_u64 v[244:245], v[4:5], 0, s[10:11]
	v_readfirstlane_b32 s10, v243
	s_mov_b32 m0, s10
	s_nop 0
	global_load_lds_dwordx4 v[244:245], off
	v_add_u32_e32 v243, 0x6000, v128
	s_mov_b64 s[10:11], 0x60000
	v_lshl_add_u64 v[244:245], v[4:5], 0, s[10:11]
	v_readfirstlane_b32 s10, v243
	s_mov_b32 m0, s10
	s_nop 0
	global_load_lds_dwordx4 v[244:245], off
	v_add_u32_e32 v243, 0x8000, v128
	s_nop 0
	v_readfirstlane_b32 s10, v243
	s_mov_b32 m0, s10
	s_nop 0
	global_load_lds_dwordx4 v[8:9], off
	v_add_u32_e32 v243, 0xa000, v128
	s_mov_b64 s[10:11], 0x20000
	v_lshl_add_u64 v[244:245], v[8:9], 0, s[10:11]
	v_readfirstlane_b32 s10, v243
	s_mov_b32 m0, s10
	s_nop 0
	global_load_lds_dwordx4 v[244:245], off
	v_add_u32_e32 v243, 0xc000, v128
	s_mov_b64 s[10:11], 0x40000
	v_lshl_add_u64 v[244:245], v[8:9], 0, s[10:11]
	v_readfirstlane_b32 s10, v243
	s_mov_b32 m0, s10
	s_nop 0
	global_load_lds_dwordx4 v[244:245], off
	v_add_u32_e32 v243, 0xe000, v128
	s_mov_b64 s[10:11], 0x60000
	v_lshl_add_u64 v[244:245], v[8:9], 0, s[10:11]
	v_readfirstlane_b32 s10, v243
	s_mov_b32 m0, s10
	s_nop 0
	global_load_lds_dwordx4 v[244:245], off
	v_bfe_u32 v12, v130, 5, 1
	v_and_b32_e32 v144, 31, v130
	v_lshlrev_b32_e32 v136, 7, v11
	v_lshrrev_b32_e32 v0, 1, v130
	v_bfe_u32 v1, v130, 1, 3
	v_bitop3_b32 v0, v12, v0, 7 bitop3:0x78
	v_lshlrev_b32_e32 v149, 4, v0
	v_bitop3_b32 v0, v12, v1, 2 bitop3:0x36
	v_lshlrev_b32_e32 v148, 4, v0
	v_bitop3_b32 v0, v12, v1, 4 bitop3:0x36
	v_or_b32_e32 v4, v136, v144
	v_lshlrev_b32_e32 v147, 4, v0
	v_bitop3_b32 v0, v12, v1, 6 bitop3:0x36
	v_lshlrev_b32_e32 v150, 7, v4
	v_lshlrev_b32_e32 v4, 5, v10
	v_lshlrev_b32_e32 v146, 4, v0
	v_bitop3_b32 v0, v13, 7, v130 bitop3:0x48
	v_and_b32_e32 v137, 0xffffffc0, v4
	v_lshlrev_b32_e32 v0, 4, v0
	v_or_b32_e32 v4, v137, v144
	v_or_b32_e32 v6, v6, v0
	v_or_b32_e32 v2, v2, v0
	v_mov_b32_e32 v32, 0
	v_and_b32_e32 v131, 63, v130
	v_lshlrev_b32_e32 v151, 7, v4
	v_add_u32_e32 v152, 0x8000, v150
	v_lshl_add_u64 v[132:133], s[48:49], 0, v[6:7]
	v_lshl_add_u64 v[134:135], s[14:15], 0, v[2:3]
	s_mov_b64 s[12:13], 0x6ff4080
	v_add_u32_e32 v246, 0x10000, v128
	v_lshl_add_u64 v[244:245], v[134:135], 0, s[90:91]
	v_readfirstlane_b32 s10, v246
	s_mov_b32 m0, s10
	s_nop 0
	global_load_lds_dwordx4 v[244:245], off
	v_add_u32_e32 v243, 0x2000, v246
	v_lshl_add_u64 v[244:245], v[134:135], 0, s[16:17]
	v_readfirstlane_b32 s10, v243
	s_mov_b32 m0, s10
	s_nop 0
	global_load_lds_dwordx4 v[244:245], off
	v_add_u32_e32 v243, 0x4000, v246
	v_lshl_add_u64 v[244:245], v[134:135], 0, s[20:21]
	v_readfirstlane_b32 s10, v243
	s_mov_b32 m0, s10
	s_nop 0
	global_load_lds_dwordx4 v[244:245], off
	v_add_u32_e32 v243, 0x6000, v246
	v_lshl_add_u64 v[244:245], v[134:135], 0, s[12:13]
	v_readfirstlane_b32 s10, v243
	s_mov_b32 m0, s10
	s_nop 0
	global_load_lds_dwordx4 v[244:245], off
	v_add_u32_e32 v243, 0x8000, v246
	s_mov_b64 s[10:11], 0x1314080
	v_lshl_add_u64 v[244:245], v[132:133], 0, s[10:11]
	v_readfirstlane_b32 s10, v243
	s_mov_b32 m0, s10
	s_nop 0
	global_load_lds_dwordx4 v[244:245], off
	v_add_u32_e32 v243, 0xa000, v246
	s_mov_b64 s[10:11], 0x1334080
	v_lshl_add_u64 v[244:245], v[132:133], 0, s[10:11]
	v_readfirstlane_b32 s10, v243
	s_mov_b32 m0, s10
	s_nop 0
	global_load_lds_dwordx4 v[244:245], off
	v_add_u32_e32 v243, 0xc000, v246
	s_mov_b64 s[10:11], 0x1354080
	v_lshl_add_u64 v[244:245], v[132:133], 0, s[10:11]
	v_readfirstlane_b32 s10, v243
	s_mov_b32 m0, s10
	s_nop 0
	global_load_lds_dwordx4 v[244:245], off
	v_add_u32_e32 v243, 0xe000, v246
	s_mov_b64 s[10:11], 0x1374080
	v_lshl_add_u64 v[244:245], v[132:133], 0, s[10:11]
	v_readfirstlane_b32 s10, v243
	s_mov_b32 m0, s10
	s_nop 0
	global_load_lds_dwordx4 v[244:245], off
	v_mov_b32_e32 v33, v32
	v_mov_b32_e32 v34, v32
	v_mov_b32_e32 v35, v32
	v_mov_b32_e32 v36, v32
	v_mov_b32_e32 v37, v32
	v_mov_b32_e32 v38, v32
	v_mov_b32_e32 v39, v32
	v_mov_b32_e32 v40, v32
	v_mov_b32_e32 v41, v32
	v_mov_b32_e32 v42, v32
	v_mov_b32_e32 v43, v32
	v_mov_b32_e32 v44, v32
	v_mov_b32_e32 v45, v32
	v_mov_b32_e32 v46, v32
	v_mov_b32_e32 v47, v32
	v_mov_b32_e32 v96, v32
	v_mov_b32_e32 v97, v32
	v_mov_b32_e32 v98, v32
	v_mov_b32_e32 v99, v32
	v_mov_b32_e32 v100, v32
	v_mov_b32_e32 v101, v32
	v_mov_b32_e32 v102, v32
	v_mov_b32_e32 v103, v32
	v_mov_b32_e32 v104, v32
	v_mov_b32_e32 v105, v32
	v_mov_b32_e32 v106, v32
	v_mov_b32_e32 v107, v32
	v_mov_b32_e32 v108, v32
	v_mov_b32_e32 v109, v32
	v_mov_b32_e32 v110, v32
	v_mov_b32_e32 v111, v32
	v_mov_b32_e32 v48, v32
	v_mov_b32_e32 v49, v32
	v_mov_b32_e32 v50, v32
	v_mov_b32_e32 v51, v32
	v_mov_b32_e32 v52, v32
	v_mov_b32_e32 v53, v32
	v_mov_b32_e32 v54, v32
	v_mov_b32_e32 v55, v32
	v_mov_b32_e32 v56, v32
	v_mov_b32_e32 v57, v32
	v_mov_b32_e32 v58, v32
	v_mov_b32_e32 v59, v32
	v_mov_b32_e32 v60, v32
	v_mov_b32_e32 v61, v32
	v_mov_b32_e32 v62, v32
	v_mov_b32_e32 v63, v32
	v_mov_b32_e32 v112, v32
	v_mov_b32_e32 v113, v32
	v_mov_b32_e32 v114, v32
	v_mov_b32_e32 v115, v32
	v_mov_b32_e32 v116, v32
	v_mov_b32_e32 v117, v32
	v_mov_b32_e32 v118, v32
	v_mov_b32_e32 v119, v32
	v_mov_b32_e32 v120, v32
	v_mov_b32_e32 v121, v32
	v_mov_b32_e32 v122, v32
	v_mov_b32_e32 v123, v32
	v_mov_b32_e32 v124, v32
	v_mov_b32_e32 v125, v32
	v_mov_b32_e32 v126, v32
	v_mov_b32_e32 v127, v32
	v_mov_b32_e32 v80, v32
	v_mov_b32_e32 v81, v32
	v_mov_b32_e32 v82, v32
	v_mov_b32_e32 v83, v32
	v_mov_b32_e32 v84, v32
	v_mov_b32_e32 v85, v32
	v_mov_b32_e32 v86, v32
	v_mov_b32_e32 v87, v32
	v_mov_b32_e32 v88, v32
	v_mov_b32_e32 v89, v32
	v_mov_b32_e32 v90, v32
	v_mov_b32_e32 v91, v32
	v_mov_b32_e32 v92, v32
	v_mov_b32_e32 v93, v32
	v_mov_b32_e32 v94, v32
	v_mov_b32_e32 v95, v32
	v_mov_b32_e32 v16, v32
	v_mov_b32_e32 v17, v32
	v_mov_b32_e32 v18, v32
	v_mov_b32_e32 v19, v32
	v_mov_b32_e32 v20, v32
	v_mov_b32_e32 v21, v32
	v_mov_b32_e32 v22, v32
	v_mov_b32_e32 v23, v32
	v_mov_b32_e32 v24, v32
	v_mov_b32_e32 v25, v32
	v_mov_b32_e32 v26, v32
	v_mov_b32_e32 v27, v32
	v_mov_b32_e32 v28, v32
	v_mov_b32_e32 v29, v32
	v_mov_b32_e32 v30, v32
	v_mov_b32_e32 v31, v32
	v_mov_b32_e32 v64, v32
	v_mov_b32_e32 v65, v32
	v_mov_b32_e32 v66, v32
	v_mov_b32_e32 v67, v32
	v_mov_b32_e32 v68, v32
	v_mov_b32_e32 v69, v32
	v_mov_b32_e32 v70, v32
	v_mov_b32_e32 v71, v32
	v_mov_b32_e32 v72, v32
	v_mov_b32_e32 v73, v32
	v_mov_b32_e32 v74, v32
	v_mov_b32_e32 v75, v32
	v_mov_b32_e32 v76, v32
	v_mov_b32_e32 v77, v32
	v_mov_b32_e32 v78, v32
	v_mov_b32_e32 v79, v32
	v_mov_b32_e32 v0, v32
	v_mov_b32_e32 v1, v32
	v_mov_b32_e32 v2, v32
	v_mov_b32_e32 v3, v32
	v_mov_b32_e32 v4, v32
	v_mov_b32_e32 v5, v32
	v_mov_b32_e32 v6, v32
	v_mov_b32_e32 v7, v32
	v_mov_b32_e32 v8, v32
	v_mov_b32_e32 v9, v32
	v_mov_b32_e32 v10, v32
	v_mov_b32_e32 v11, v32
	v_mov_b32_e32 v12, v32
	v_mov_b32_e32 v13, v32
	v_mov_b32_e32 v14, v32
	v_mov_b32_e32 v15, v32
	s_and_saveexec_b64 s[4:5], vcc
	s_xor_b64 s[4:5], exec, s[4:5]
	s_cbranch_execz .LBB0_1372
	s_lshl_b32 s3, s8, 10
	s_and_b32 s3, s3, 0xfffff000
	s_addk_i32 s3, 0xd000
	s_cmp_gt_i32 s8, 15
	s_cselect_b32 s72, s3, 0
	s_lshl_b64 s[10:11], s[72:73], 2
	s_add_u32 s9, s1, s10
	s_addc_u32 s12, s6, s11
	s_ashr_i32 s3, s2, 31
	s_lshl_b64 s[10:11], s[2:3], 2
	s_add_u32 s10, s9, s10
	s_addc_u32 s11, s12, s11
	v_mov_b32_e32 v131, v129
	v_lshl_add_u64 v[182:183], v[130:131], 2, s[10:11]
	v_add_co_u32_e32 v182, vcc, 0x147000, v182
	s_nop 1
	v_addc_co_u32_e32 v183, vcc, 0, v183, vcc
	global_load_dword v182, v[182:183], off offset:3072

.LBB0_1374:
	s_or_b64 exec, exec, s[4:5]
	v_lshl_add_u32 v183, v130, 2, v167
	s_waitcnt vmcnt(0)
	ds_write_b32 v183, v182
	v_and_b32_e32 v131, 63, v130
	s_mov_b32 s8, 0
	s_mov_b64 s[4:5], 0
	s_mov_b64 s[12:13], 0x6ff4080
	s_branch .LLBB01375_entry
.Lnodma_LBB01375:
	v_mfma_f32_32x32x16_bf16 v[80:95], v[190:193], v[198:201], v[80:95]
	v_mfma_f32_32x32x16_bf16 v[16:31], v[190:193], v[202:205], v[16:31]
	v_mfma_f32_32x32x16_bf16 v[64:79], v[194:197], v[198:201], v[64:79]
	v_mfma_f32_32x32x16_bf16 v[0:15], v[194:197], v[202:205], v[0:15]
	s_waitcnt lgkmcnt(0)
	s_nop 0
	v_mfma_f32_32x32x16_bf16 v[112:127], v[206:209], v[222:225], v[112:127]
	v_mfma_f32_32x32x16_bf16 v[48:63], v[206:209], v[226:229], v[48:63]
	v_mfma_f32_32x32x16_bf16 v[96:111], v[210:213], v[222:225], v[96:111]
	v_mfma_f32_32x32x16_bf16 v[32:47], v[210:213], v[226:229], v[32:47]
	v_mfma_f32_32x32x16_bf16 v[80:95], v[214:217], v[222:225], v[80:95]
	v_mfma_f32_32x32x16_bf16 v[16:31], v[214:217], v[226:229], v[16:31]
	v_mfma_f32_32x32x16_bf16 v[64:79], v[218:221], v[222:225], v[64:79]
	v_mfma_f32_32x32x16_bf16 v[0:15], v[218:221], v[226:229], v[0:15]
	s_branch .Ljoin_LBB01375
.LLBB01375_entry:
.LBB0_1375:
	s_add_i32 s9, s8, 0x10000
	s_and_b32 s10, s8, 0x10000
	v_add_u32_e32 v246, s10, v128
	s_waitcnt vmcnt(8) lgkmcnt(0)
	s_barrier
	s_and_b32 s8, s8, 0x10000
	v_add_u32_e32 v153, s8, v152
	v_add_u32_e32 v181, v153, v149
	ds_read_b128 v[182:185], v181 offset:0
	ds_read_b128 v[186:189], v181 offset:0x1000
	ds_read_b128 v[190:193], v181 offset:0x2000
	v_add_u32_e32 v154, s8, v151
	ds_read_b128 v[194:197], v181 offset:0x3000
	v_add_u32_e32 v181, v154, v149
	ds_read_b128 v[198:201], v181 offset:0
	ds_read_b128 v[202:205], v181 offset:0x1000
	v_add_u32_e32 v181, v153, v148
	ds_read_b128 v[206:209], v181 offset:0
	ds_read_b128 v[210:213], v181 offset:0x1000
	ds_read_b128 v[214:217], v181 offset:0x2000
	ds_read_b128 v[218:221], v181 offset:0x3000
	v_add_u32_e32 v181, v154, v148
	ds_read_b128 v[222:225], v181 offset:0
	ds_read_b128 v[226:229], v181 offset:0x1000
	s_waitcnt lgkmcnt(6)
	s_nop 0
	v_mfma_f32_32x32x16_bf16 v[112:127], v[182:185], v[198:201], v[112:127]
	v_mfma_f32_32x32x16_bf16 v[48:63], v[182:185], v[202:205], v[48:63]
	v_mfma_f32_32x32x16_bf16 v[96:111], v[186:189], v[198:201], v[96:111]
	v_mfma_f32_32x32x16_bf16 v[32:47], v[186:189], v[202:205], v[32:47]
	v_mfma_f32_32x32x16_bf16 v[80:95], v[190:193], v[198:201], v[80:95]
	v_mfma_f32_32x32x16_bf16 v[16:31], v[190:193], v[202:205], v[16:31]
	v_mfma_f32_32x32x16_bf16 v[64:79], v[194:197], v[198:201], v[64:79]
	v_mfma_f32_32x32x16_bf16 v[0:15], v[194:197], v[202:205], v[0:15]
	v_add_u32_e32 v181, v153, v147
	ds_read_b128 v[182:185], v181 offset:0
	ds_read_b128 v[186:189], v181 offset:0x1000
	ds_read_b128 v[190:193], v181 offset:0x2000
	ds_read_b128 v[194:197], v181 offset:0x3000
	v_add_u32_e32 v181, v154, v147
	ds_read_b128 v[198:201], v181 offset:0
	ds_read_b128 v[202:205], v181 offset:0x1000
	s_waitcnt lgkmcnt(6)
	s_nop 0
	v_mfma_f32_32x32x16_bf16 v[112:127], v[206:209], v[222:225], v[112:127]
	v_mfma_f32_32x32x16_bf16 v[48:63], v[206:209], v[226:229], v[48:63]
	v_mfma_f32_32x32x16_bf16 v[96:111], v[210:213], v[222:225], v[96:111]
	v_mfma_f32_32x32x16_bf16 v[32:47], v[210:213], v[226:229], v[32:47]
	v_mfma_f32_32x32x16_bf16 v[80:95], v[214:217], v[222:225], v[80:95]
	v_mfma_f32_32x32x16_bf16 v[16:31], v[214:217], v[226:229], v[16:31]
	v_mfma_f32_32x32x16_bf16 v[64:79], v[218:221], v[222:225], v[64:79]
	v_mfma_f32_32x32x16_bf16 v[0:15], v[218:221], v[226:229], v[0:15]
	v_add_u32_e32 v153, v153, v146
	ds_read_b128 v[206:209], v153 offset:0
	ds_read_b128 v[210:213], v153 offset:0x1000
	ds_read_b128 v[214:217], v153 offset:0x2000
	ds_read_b128 v[218:221], v153 offset:0x3000
	v_add_u32_e32 v153, v154, v146
	ds_read_b128 v[222:225], v153 offset:0
	ds_read_b128 v[226:229], v153 offset:0x1000
	s_waitcnt lgkmcnt(6)
	s_nop 0
	v_mfma_f32_32x32x16_bf16 v[112:127], v[182:185], v[198:201], v[112:127]
	v_mfma_f32_32x32x16_bf16 v[48:63], v[182:185], v[202:205], v[48:63]
	v_mfma_f32_32x32x16_bf16 v[96:111], v[186:189], v[198:201], v[96:111]
	v_mfma_f32_32x32x16_bf16 v[32:47], v[186:189], v[202:205], v[32:47]
	s_waitcnt lgkmcnt(0)
	s_barrier
	s_add_u32 s4, s4, 0x80
	s_addc_u32 s5, s5, 0
	s_cmpk_eq_i32 s4, 0x780
	s_cbranch_scc1 .Lnodma_LBB01375
	v_mfma_f32_32x32x16_bf16 v[80:95], v[190:193], v[198:201], v[80:95]
	v_lshl_add_u64 v[244:245], v[134:135], 0, s[4:5]
	v_lshl_add_u64 v[244:245], v[244:245], 0, s[90:91]
	v_readfirstlane_b32 s10, v246
	s_mov_b32 m0, s10
	s_nop 0
	global_load_lds_dwordx4 v[244:245], off
	v_mfma_f32_32x32x16_bf16 v[16:31], v[190:193], v[202:205], v[16:31]
	v_add_u32_e32 v243, 0x2000, v246
	v_lshl_add_u64 v[244:245], v[134:135], 0, s[4:5]
	v_lshl_add_u64 v[244:245], v[244:245], 0, s[16:17]
	v_readfirstlane_b32 s10, v243
	s_mov_b32 m0, s10
	s_nop 0
	global_load_lds_dwordx4 v[244:245], off
	v_mfma_f32_32x32x16_bf16 v[64:79], v[194:197], v[198:201], v[64:79]
	v_add_u32_e32 v243, 0x4000, v246
	v_lshl_add_u64 v[244:245], v[134:135], 0, s[4:5]
	v_lshl_add_u64 v[244:245], v[244:245], 0, s[20:21]
	v_readfirstlane_b32 s10, v243
	s_mov_b32 m0, s10
	s_nop 0
	global_load_lds_dwordx4 v[244:245], off
	v_mfma_f32_32x32x16_bf16 v[0:15], v[194:197], v[202:205], v[0:15]
	v_add_u32_e32 v243, 0x6000, v246
	v_lshl_add_u64 v[244:245], v[134:135], 0, s[4:5]
	v_lshl_add_u64 v[244:245], v[244:245], 0, s[12:13]
	v_readfirstlane_b32 s10, v243
	s_mov_b32 m0, s10
	s_nop 0
	global_load_lds_dwordx4 v[244:245], off
	s_waitcnt lgkmcnt(0)
	s_nop 0
	v_mfma_f32_32x32x16_bf16 v[112:127], v[206:209], v[222:225], v[112:127]
	v_add_u32_e32 v243, 0x8000, v246
	s_mov_b64 s[10:11], 0x1314080
	v_lshl_add_u64 v[244:245], v[132:133], 0, s[4:5]
	v_lshl_add_u64 v[244:245], v[244:245], 0, s[10:11]
	v_readfirstlane_b32 s10, v243
	s_mov_b32 m0, s10
	s_nop 0
	global_load_lds_dwordx4 v[244:245], off
	v_mfma_f32_32x32x16_bf16 v[48:63], v[206:209], v[226:229], v[48:63]
	v_add_u32_e32 v243, 0xa000, v246
	s_mov_b64 s[10:11], 0x1334080
	v_lshl_add_u64 v[244:245], v[132:133], 0, s[4:5]
	v_lshl_add_u64 v[244:245], v[244:245], 0, s[10:11]
	v_readfirstlane_b32 s10, v243
	s_mov_b32 m0, s10
	s_nop 0
	global_load_lds_dwordx4 v[244:245], off
	v_mfma_f32_32x32x16_bf16 v[96:111], v[210:213], v[222:225], v[96:111]
	v_add_u32_e32 v243, 0xc000, v246
	s_mov_b64 s[10:11], 0x1354080
	v_lshl_add_u64 v[244:245], v[132:133], 0, s[4:5]
	v_lshl_add_u64 v[244:245], v[244:245], 0, s[10:11]
	v_readfirstlane_b32 s10, v243
	s_mov_b32 m0, s10
	s_nop 0
	global_load_lds_dwordx4 v[244:245], off
	v_mfma_f32_32x32x16_bf16 v[32:47], v[210:213], v[226:229], v[32:47]
	v_add_u32_e32 v243, 0xe000, v246
	s_mov_b64 s[10:11], 0x1374080
	v_lshl_add_u64 v[244:245], v[132:133], 0, s[4:5]
	v_lshl_add_u64 v[244:245], v[244:245], 0, s[10:11]
	v_readfirstlane_b32 s10, v243
	s_mov_b32 m0, s10
	s_nop 0
	global_load_lds_dwordx4 v[244:245], off
	v_mfma_f32_32x32x16_bf16 v[80:95], v[214:217], v[222:225], v[80:95]
	v_mfma_f32_32x32x16_bf16 v[16:31], v[214:217], v[226:229], v[16:31]
	v_mfma_f32_32x32x16_bf16 v[64:79], v[218:221], v[222:225], v[64:79]
	v_mfma_f32_32x32x16_bf16 v[0:15], v[218:221], v[226:229], v[0:15]
.Ljoin_LBB01375:
	s_cmpk_lg_i32 s4, 0x780
	s_mov_b32 s8, s9
	s_cbranch_scc1 .LBB0_1375
	s_waitcnt vmcnt(0)
	s_waitcnt vmcnt(0) lgkmcnt(0)
	s_barrier
	v_add_u32_e32 v154, 0x18000, v150
	v_add_u32_e32 v186, v154, v149
	ds_read_b128 v[132:135], v186 offset:0
	v_add_u32_e32 v181, 0x10000, v151
	ds_read_b128 v[150:153], v186 offset:0x1000
	ds_read_b128 v[182:185], v186 offset:0x2000
	ds_read_b128 v[186:189], v186 offset:0x3000
	v_add_u32_e32 v149, v181, v149
	ds_read_b128 v[190:193], v149 offset:0
	ds_read_b128 v[194:197], v149 offset:0x1000
	v_add_u32_e32 v149, v154, v148
	ds_read_b128 v[198:201], v149 offset:0
	ds_read_b128 v[202:205], v149 offset:0x1000
	ds_read_b128 v[206:209], v149 offset:0x2000
	ds_read_b128 v[210:213], v149 offset:0x3000
	v_add_u32_e32 v148, v181, v148
	ds_read_b128 v[214:217], v148 offset:0
	ds_read_b128 v[218:221], v148 offset:0x1000
	s_waitcnt lgkmcnt(6)
	s_nop 0
	v_mfma_f32_32x32x16_bf16 v[112:127], v[132:135], v[190:193], v[112:127]
	v_mfma_f32_32x32x16_bf16 v[48:63], v[132:135], v[194:197], v[48:63]
	v_mfma_f32_32x32x16_bf16 v[96:111], v[150:153], v[190:193], v[96:111]
	v_mfma_f32_32x32x16_bf16 v[32:47], v[150:153], v[194:197], v[32:47]
	v_mfma_f32_32x32x16_bf16 v[80:95], v[182:185], v[190:193], v[80:95]
	v_mfma_f32_32x32x16_bf16 v[16:31], v[182:185], v[194:197], v[16:31]
	v_mfma_f32_32x32x16_bf16 v[64:79], v[186:189], v[190:193], v[64:79]
	v_mfma_f32_32x32x16_bf16 v[0:15], v[186:189], v[194:197], v[0:15]
	v_add_u32_e32 v152, v154, v147
	ds_read_b128 v[132:135], v152 offset:0
	ds_read_b128 v[148:151], v152 offset:0x1000
	ds_read_b128 v[182:185], v152 offset:0x2000
	ds_read_b128 v[186:189], v152 offset:0x3000
	v_add_u32_e32 v147, v181, v147
	ds_read_b128 v[190:193], v147 offset:0
	ds_read_b128 v[194:197], v147 offset:0x1000
	s_waitcnt lgkmcnt(6)
	s_nop 0
	v_mfma_f32_32x32x16_bf16 v[112:127], v[198:201], v[214:217], v[112:127]
	v_mfma_f32_32x32x16_bf16 v[48:63], v[198:201], v[218:221], v[48:63]
	v_mfma_f32_32x32x16_bf16 v[96:111], v[202:205], v[214:217], v[96:111]
	v_mfma_f32_32x32x16_bf16 v[32:47], v[202:205], v[218:221], v[32:47]
	v_mfma_f32_32x32x16_bf16 v[80:95], v[206:209], v[214:217], v[80:95]
	v_mfma_f32_32x32x16_bf16 v[16:31], v[206:209], v[218:221], v[16:31]
	v_mfma_f32_32x32x16_bf16 v[64:79], v[210:213], v[214:217], v[64:79]
	v_mfma_f32_32x32x16_bf16 v[0:15], v[210:213], v[218:221], v[0:15]
	v_add_u32_e32 v147, v154, v146
	ds_read_b128 v[198:201], v147 offset:0
	ds_read_b128 v[202:205], v147 offset:0x1000
	ds_read_b128 v[206:209], v147 offset:0x2000
	ds_read_b128 v[210:213], v147 offset:0x3000
	v_add_u32_e32 v146, v181, v146
	ds_read_b128 v[214:217], v146 offset:0
	ds_read_b128 v[218:221], v146 offset:0x1000
	s_waitcnt lgkmcnt(6)
	s_nop 0
	v_mfma_f32_32x32x16_bf16 v[112:127], v[132:135], v[190:193], v[112:127]
	v_mfma_f32_32x32x16_bf16 v[48:63], v[132:135], v[194:197], v[48:63]
	v_mfma_f32_32x32x16_bf16 v[96:111], v[148:151], v[190:193], v[96:111]
	v_mfma_f32_32x32x16_bf16 v[32:47], v[148:151], v[194:197], v[32:47]
	v_mfma_f32_32x32x16_bf16 v[80:95], v[182:185], v[190:193], v[80:95]
	v_mfma_f32_32x32x16_bf16 v[16:31], v[182:185], v[194:197], v[16:31]
	v_mfma_f32_32x32x16_bf16 v[64:79], v[186:189], v[190:193], v[64:79]
	v_mfma_f32_32x32x16_bf16 v[0:15], v[186:189], v[194:197], v[0:15]
	s_waitcnt lgkmcnt(0)
	s_nop 0
	v_mfma_f32_32x32x16_bf16 v[112:127], v[198:201], v[214:217], v[112:127]
	v_mfma_f32_32x32x16_bf16 v[48:63], v[198:201], v[218:221], v[48:63]
	v_mfma_f32_32x32x16_bf16 v[96:111], v[202:205], v[214:217], v[96:111]
	v_mfma_f32_32x32x16_bf16 v[32:47], v[202:205], v[218:221], v[32:47]
	v_mfma_f32_32x32x16_bf16 v[80:95], v[206:209], v[214:217], v[80:95]
	v_mfma_f32_32x32x16_bf16 v[16:31], v[206:209], v[218:221], v[16:31]
	v_mfma_f32_32x32x16_bf16 v[64:79], v[210:213], v[214:217], v[64:79]
	v_mfma_f32_32x32x16_bf16 v[0:15], v[210:213], v[218:221], v[0:15]
	v_lshrrev_b32_e32 v130, 3, v130
	v_lshlrev_b32_e32 v132, 2, v137
	v_lshlrev_b32_e32 v133, 2, v144
	s_mov_b32 s4, 0x24000
	v_and_b32_e32 v147, 4, v130
	v_add3_u32 v146, v132, v133, s4
	v_lshlrev_b32_e32 v130, 2, v136
	v_lshlrev_b32_e32 v132, 2, v147
	s_mov_b32 s4, 0x24400
	s_barrier
	v_add3_u32 v130, v130, v132, s4
	ds_read_b32 v148, v146
	ds_read_b128 v[132:135], v130
	s_movk_i32 s4, 0x2400
	v_mul_lo_u32 v145, v145, s4
	s_movk_i32 s4, 0x110
	v_mad_u32_u24 v144, v144, s4, v145
	s_waitcnt lgkmcnt(0)
	v_fma_f32 v112, v112, v148, v132
	v_fma_f32 v113, v113, v148, v133
	v_max_f32_e32 v112, 0, v112
	v_max_f32_e32 v113, 0, v113
	v_fma_f32 v114, v114, v148, v134
	v_fmac_f32_e32 v135, v115, v148
	v_max_f32_e32 v132, 0, v114
	v_max_f32_e32 v115, 0, v135
	v_mul_f32_e32 v112, v112, v112
	v_mul_f32_e32 v113, v113, v113
	v_cvt_pk_bf16_f32 v114, v112, v113
	v_mul_f32_e32 v112, v132, v132
	v_mul_f32_e32 v113, v115, v115
	v_cvt_pk_bf16_f32 v115, v112, v113
	v_lshl_or_b32 v112, v147, 1, v144
	ds_write_b64 v112, v[114:115]
	ds_read_b128 v[132:135], v130 offset:32
	v_and_b32_e32 v128, 0xf0, v128
	s_add_i32 s7, s7, s38
	s_cmpk_gt_i32 s7, 0x2ff
	s_waitcnt lgkmcnt(0)
	v_fma_f32 v113, v116, v148, v132
	v_fma_f32 v114, v117, v148, v133
	v_max_f32_e32 v113, 0, v113
	v_max_f32_e32 v114, 0, v114
	v_fma_f32 v115, v118, v148, v134
	v_fmac_f32_e32 v135, v119, v148
	v_max_f32_e32 v115, 0, v115
	v_max_f32_e32 v116, 0, v135
	v_mul_f32_e32 v113, v113, v113
	v_mul_f32_e32 v114, v114, v114
	v_cvt_pk_bf16_f32 v114, v113, v114
	v_mul_f32_e32 v113, v115, v115
	v_mul_f32_e32 v115, v116, v116
	v_cvt_pk_bf16_f32 v115, v113, v115
	ds_write_b64 v112, v[114:115] offset:16
	ds_read_b128 v[114:117], v130 offset:64
	s_waitcnt lgkmcnt(0)
	v_fma_f32 v113, v120, v148, v114
	v_fma_f32 v114, v121, v148, v115
	v_max_f32_e32 v113, 0, v113
	v_max_f32_e32 v114, 0, v114
	v_fma_f32 v115, v122, v148, v116
	v_fmac_f32_e32 v117, v123, v148
	v_max_f32_e32 v115, 0, v115
	v_max_f32_e32 v116, 0, v117
	v_mul_f32_e32 v113, v113, v113
	v_mul_f32_e32 v114, v114, v114
	v_cvt_pk_bf16_f32 v114, v113, v114
	v_mul_f32_e32 v113, v115, v115
	v_mul_f32_e32 v115, v116, v116
	v_cvt_pk_bf16_f32 v115, v113, v115
	ds_write_b64 v112, v[114:115] offset:32
	ds_read_b128 v[114:117], v130 offset:96
	s_waitcnt lgkmcnt(0)
	v_fma_f32 v113, v124, v148, v114
	v_fma_f32 v114, v125, v148, v115
	v_max_f32_e32 v113, 0, v113
	v_max_f32_e32 v114, 0, v114
	v_fma_f32 v115, v126, v148, v116
	v_fmac_f32_e32 v117, v127, v148
	v_max_f32_e32 v115, 0, v115
	v_max_f32_e32 v116, 0, v117
	v_mul_f32_e32 v113, v113, v113
	v_mul_f32_e32 v114, v114, v114
	v_cvt_pk_bf16_f32 v114, v113, v114
	v_mul_f32_e32 v113, v115, v115
	v_mul_f32_e32 v115, v116, v116
	v_cvt_pk_bf16_f32 v115, v113, v115
	ds_write_b64 v112, v[114:115] offset:48
	ds_read_b128 v[114:117], v130 offset:128
	s_waitcnt lgkmcnt(0)
	v_fma_f32 v96, v96, v148, v114
	v_fma_f32 v97, v97, v148, v115
	v_max_f32_e32 v96, 0, v96
	v_max_f32_e32 v97, 0, v97
	v_fma_f32 v98, v98, v148, v116
	v_fmac_f32_e32 v117, v99, v148
	v_max_f32_e32 v98, 0, v98
	v_max_f32_e32 v99, 0, v117
	v_mul_f32_e32 v96, v96, v96
	v_mul_f32_e32 v97, v97, v97
	v_cvt_pk_bf16_f32 v96, v96, v97
	v_mul_f32_e32 v97, v98, v98
	v_mul_f32_e32 v98, v99, v99
	v_cvt_pk_bf16_f32 v97, v97, v98
	ds_write_b64 v112, v[96:97] offset:64
	ds_read_b128 v[96:99], v130 offset:160
	s_waitcnt lgkmcnt(0)
	v_fma_f32 v96, v100, v148, v96
	v_fma_f32 v97, v101, v148, v97
	v_max_f32_e32 v96, 0, v96
	v_max_f32_e32 v97, 0, v97
	v_fma_f32 v98, v102, v148, v98
	v_fmac_f32_e32 v99, v103, v148
	v_max_f32_e32 v98, 0, v98
	v_max_f32_e32 v99, 0, v99
	v_mul_f32_e32 v96, v96, v96
	v_mul_f32_e32 v97, v97, v97
	v_cvt_pk_bf16_f32 v96, v96, v97
	v_mul_f32_e32 v97, v98, v98
	v_mul_f32_e32 v98, v99, v99
	v_cvt_pk_bf16_f32 v97, v97, v98
	ds_write_b64 v112, v[96:97] offset:80
	ds_read_b128 v[96:99], v130 offset:192
	v_add_u32_e32 v102, s2, v136
	v_ashrrev_i32_e32 v103, 31, v102
	s_waitcnt lgkmcnt(0)
	v_fma_f32 v96, v104, v148, v96
	v_fma_f32 v97, v105, v148, v97
	v_max_f32_e32 v96, 0, v96
	v_max_f32_e32 v97, 0, v97
	v_fma_f32 v98, v106, v148, v98
	v_fmac_f32_e32 v99, v107, v148
	v_max_f32_e32 v98, 0, v98
	v_max_f32_e32 v99, 0, v99
	v_mul_f32_e32 v96, v96, v96
	v_mul_f32_e32 v97, v97, v97
	v_cvt_pk_bf16_f32 v96, v96, v97
	v_mul_f32_e32 v97, v98, v98
	v_mul_f32_e32 v98, v99, v99
	v_cvt_pk_bf16_f32 v97, v97, v98
	ds_write_b64 v112, v[96:97] offset:96
	ds_read_b128 v[96:99], v130 offset:224
	v_add_u32_e32 v106, s3, v137
	v_lshrrev_b32_e32 v107, 4, v131
	s_waitcnt lgkmcnt(0)
	v_fma_f32 v96, v108, v148, v96
	v_fma_f32 v97, v109, v148, v97
	v_max_f32_e32 v96, 0, v96
	v_max_f32_e32 v97, 0, v97
	v_fma_f32 v98, v110, v148, v98
	v_fmac_f32_e32 v99, v111, v148
	v_max_f32_e32 v98, 0, v98
	v_max_f32_e32 v99, 0, v99
	v_mul_f32_e32 v96, v96, v96
	v_mul_f32_e32 v97, v97, v97
	v_cvt_pk_bf16_f32 v96, v96, v97
	v_mul_f32_e32 v97, v98, v98
	v_mul_f32_e32 v98, v99, v99
	v_cvt_pk_bf16_f32 v97, v97, v98
	ds_write_b64 v112, v[96:97] offset:112
	ds_read_b128 v[96:99], v130 offset:256
	s_waitcnt lgkmcnt(0)
	v_fma_f32 v80, v80, v148, v96
	v_fma_f32 v81, v81, v148, v97
	v_max_f32_e32 v80, 0, v80
	v_max_f32_e32 v81, 0, v81
	v_fma_f32 v82, v82, v148, v98
	v_fmac_f32_e32 v99, v83, v148
	v_max_f32_e32 v82, 0, v82
	v_max_f32_e32 v83, 0, v99
	v_mul_f32_e32 v80, v80, v80
	v_mul_f32_e32 v81, v81, v81
	v_cvt_pk_bf16_f32 v80, v80, v81
	v_mul_f32_e32 v81, v82, v82
	v_mul_f32_e32 v82, v83, v83
	v_cvt_pk_bf16_f32 v81, v81, v82
	ds_write_b64 v112, v[80:81] offset:128
	ds_read_b128 v[80:83], v130 offset:288
	s_waitcnt lgkmcnt(0)
	v_fma_f32 v80, v84, v148, v80
	v_fma_f32 v81, v85, v148, v81
	v_max_f32_e32 v80, 0, v80
	v_max_f32_e32 v81, 0, v81
	v_fma_f32 v82, v86, v148, v82
	v_fmac_f32_e32 v83, v87, v148
	v_max_f32_e32 v82, 0, v82
	v_max_f32_e32 v83, 0, v83
	v_mul_f32_e32 v80, v80, v80
	v_mul_f32_e32 v81, v81, v81
	v_cvt_pk_bf16_f32 v80, v80, v81
	v_mul_f32_e32 v81, v82, v82
	v_mul_f32_e32 v82, v83, v83
	v_cvt_pk_bf16_f32 v81, v81, v82
	ds_write_b64 v112, v[80:81] offset:144
	ds_read_b128 v[80:83], v130 offset:320
	s_waitcnt lgkmcnt(0)
	v_fma_f32 v80, v88, v148, v80
	v_fma_f32 v81, v89, v148, v81
	v_max_f32_e32 v80, 0, v80
	v_max_f32_e32 v81, 0, v81
	v_fma_f32 v82, v90, v148, v82
	v_fmac_f32_e32 v83, v91, v148
	v_max_f32_e32 v82, 0, v82
	v_max_f32_e32 v83, 0, v83
	v_mul_f32_e32 v80, v80, v80
	v_mul_f32_e32 v81, v81, v81
	v_cvt_pk_bf16_f32 v80, v80, v81
	v_mul_f32_e32 v81, v82, v82
	v_mul_f32_e32 v82, v83, v83
	v_cvt_pk_bf16_f32 v81, v81, v82
	ds_write_b64 v112, v[80:81] offset:160
	ds_read_b128 v[80:83], v130 offset:352
	s_waitcnt lgkmcnt(0)
	v_fma_f32 v80, v92, v148, v80
	v_fma_f32 v81, v93, v148, v81
	v_max_f32_e32 v80, 0, v80
	v_max_f32_e32 v81, 0, v81
	v_fma_f32 v82, v94, v148, v82
	v_fmac_f32_e32 v83, v95, v148
	v_max_f32_e32 v82, 0, v82
	v_max_f32_e32 v83, 0, v83
	v_mul_f32_e32 v80, v80, v80
	v_mul_f32_e32 v81, v81, v81
	v_cvt_pk_bf16_f32 v80, v80, v81
	v_mul_f32_e32 v81, v82, v82
	v_mul_f32_e32 v82, v83, v83
	v_cvt_pk_bf16_f32 v81, v81, v82
	ds_write_b64 v112, v[80:81] offset:176
	ds_read_b128 v[80:83], v130 offset:384
	s_waitcnt lgkmcnt(0)
	v_fma_f32 v64, v64, v148, v80
	v_fma_f32 v65, v65, v148, v81
	v_max_f32_e32 v64, 0, v64
	v_max_f32_e32 v65, 0, v65
	v_fma_f32 v66, v66, v148, v82
	v_fmac_f32_e32 v83, v67, v148
	v_max_f32_e32 v66, 0, v66
	v_max_f32_e32 v67, 0, v83
	v_mul_f32_e32 v64, v64, v64
	v_mul_f32_e32 v65, v65, v65
	v_cvt_pk_bf16_f32 v64, v64, v65
	v_mul_f32_e32 v65, v66, v66
	v_mul_f32_e32 v66, v67, v67
	v_cvt_pk_bf16_f32 v65, v65, v66
	ds_write_b64 v112, v[64:65] offset:192
	ds_read_b128 v[64:67], v130 offset:416
	s_waitcnt lgkmcnt(0)
	v_fma_f32 v64, v68, v148, v64
	v_fma_f32 v65, v69, v148, v65
	v_max_f32_e32 v64, 0, v64
	v_max_f32_e32 v65, 0, v65
	v_fma_f32 v66, v70, v148, v66
	v_fmac_f32_e32 v67, v71, v148
	v_max_f32_e32 v66, 0, v66
	v_max_f32_e32 v67, 0, v67
	v_mul_f32_e32 v64, v64, v64
	v_mul_f32_e32 v65, v65, v65
	v_cvt_pk_bf16_f32 v64, v64, v65
	v_mul_f32_e32 v65, v66, v66
	v_mul_f32_e32 v66, v67, v67
	v_cvt_pk_bf16_f32 v65, v65, v66
	ds_write_b64 v112, v[64:65] offset:208
	ds_read_b128 v[64:67], v130 offset:448
	v_or_b32_e32 v68, v145, v128
	v_mad_u32_u24 v108, v107, s4, v68
	s_waitcnt lgkmcnt(0)
	v_fma_f32 v64, v72, v148, v64
	v_fma_f32 v65, v73, v148, v65
	v_max_f32_e32 v64, 0, v64
	v_max_f32_e32 v65, 0, v65
	v_fma_f32 v66, v74, v148, v66
	v_fmac_f32_e32 v67, v75, v148
	v_max_f32_e32 v66, 0, v66
	v_max_f32_e32 v67, 0, v67
	v_mul_f32_e32 v64, v64, v64
	v_mul_f32_e32 v65, v65, v65
	v_cvt_pk_bf16_f32 v64, v64, v65
	v_mul_f32_e32 v65, v66, v66
	v_mul_f32_e32 v66, v67, v67
	v_cvt_pk_bf16_f32 v65, v65, v66
	ds_write_b64 v112, v[64:65] offset:224
	ds_read_b128 v[64:67], v130 offset:480
	s_waitcnt lgkmcnt(0)
	v_fma_f32 v64, v76, v148, v64
	v_fma_f32 v65, v77, v148, v65
	v_max_f32_e32 v64, 0, v64
	v_max_f32_e32 v65, 0, v65
	v_fma_f32 v66, v78, v148, v66
	v_fmac_f32_e32 v67, v79, v148
	v_max_f32_e32 v66, 0, v66
	v_max_f32_e32 v67, 0, v67
	v_mul_f32_e32 v64, v64, v64
	v_mul_f32_e32 v65, v65, v65
	v_cvt_pk_bf16_f32 v64, v64, v65
	v_mul_f32_e32 v65, v66, v66
	v_mul_f32_e32 v66, v67, v67
	v_cvt_pk_bf16_f32 v65, v65, v66
	ds_write_b64 v112, v[64:65] offset:240
	v_or_b32_e32 v64, v106, v107
	v_or_b32_e32 v77, 4, v107
	v_ashrrev_i32_e32 v65, 31, v64
	v_mad_u32_u24 v76, v77, s4, v68
	v_lshlrev_b64 v[104:105], 13, v[64:65]
	ds_read_b128 v[78:81], v76 offset:1088
	ds_read_b128 v[82:85], v76 offset:2176
	ds_read_b128 v[86:89], v108
	ds_read_b32 v109, v146 offset:128
	ds_read_b128 v[90:93], v76
	ds_read_b128 v[94:97], v130
	ds_read_b128 v[98:101], v76 offset:3264
	ds_read_b128 v[72:75], v76 offset:4352
	ds_read_b128 v[68:71], v76 offset:5440
	ds_read_b128 v[64:67], v76 offset:6528
	s_waitcnt lgkmcnt(4)
	v_fma_f32 v48, v48, v109, v94
	v_fma_f32 v49, v49, v109, v95
	v_max_f32_e32 v48, 0, v48
	v_max_f32_e32 v49, 0, v49
	v_fma_f32 v50, v50, v109, v96
	v_fmac_f32_e32 v97, v51, v109
	v_max_f32_e32 v50, 0, v50
	v_max_f32_e32 v51, 0, v97
	v_mul_f32_e32 v48, v48, v48
	v_mul_f32_e32 v49, v49, v49
	v_cvt_pk_bf16_f32 v48, v48, v49
	v_mul_f32_e32 v49, v50, v50
	v_mul_f32_e32 v50, v51, v51
	v_cvt_pk_bf16_f32 v49, v49, v50
	ds_write_b64 v112, v[48:49]
	ds_read_b128 v[94:97], v130 offset:32
	v_lshl_add_u64 v[50:51], s[42:43], 0, v[104:105]
	v_lshlrev_b64 v[48:49], 1, v[102:103]
	v_lshl_add_u64 v[50:51], v[50:51], 0, v[48:49]
	v_lshl_add_u64 v[102:103], v[50:51], 0, v[128:129]
	s_waitcnt lgkmcnt(0)
	v_fma_f32 v50, v52, v109, v94
	v_fma_f32 v51, v53, v109, v95
	v_max_f32_e32 v50, 0, v50
	v_max_f32_e32 v51, 0, v51
	v_fma_f32 v52, v54, v109, v96
	v_fmac_f32_e32 v97, v55, v109
	v_max_f32_e32 v52, 0, v52
	v_max_f32_e32 v53, 0, v97
	v_mul_f32_e32 v50, v50, v50
	v_mul_f32_e32 v51, v51, v51
	v_cvt_pk_bf16_f32 v50, v50, v51
	v_mul_f32_e32 v51, v52, v52
	v_mul_f32_e32 v52, v53, v53
	v_cvt_pk_bf16_f32 v51, v51, v52
	ds_write_b64 v112, v[50:51] offset:16
	ds_read_b128 v[50:53], v130 offset:64
	v_or_b32_e32 v54, v106, v77
	v_ashrrev_i32_e32 v55, 31, v54
	v_lshlrev_b64 v[54:55], 13, v[54:55]
	v_lshl_add_u64 v[54:55], s[42:43], 0, v[54:55]
	s_waitcnt lgkmcnt(0)
	v_fma_f32 v50, v56, v109, v50
	v_fma_f32 v51, v57, v109, v51
	v_max_f32_e32 v50, 0, v50
	v_max_f32_e32 v51, 0, v51
	v_fma_f32 v52, v58, v109, v52
	v_fmac_f32_e32 v53, v59, v109
	v_max_f32_e32 v52, 0, v52
	v_max_f32_e32 v53, 0, v53
	v_mul_f32_e32 v50, v50, v50
	v_mul_f32_e32 v51, v51, v51
	v_cvt_pk_bf16_f32 v50, v50, v51
	v_mul_f32_e32 v51, v52, v52
	v_mul_f32_e32 v52, v53, v53
	v_cvt_pk_bf16_f32 v51, v51, v52
	ds_write_b64 v112, v[50:51] offset:32
	ds_read_b128 v[50:53], v130 offset:96
	v_or_b32_e32 v56, 8, v107
	v_lshl_add_u64 v[54:55], v[54:55], 0, v[48:49]
	v_lshl_add_u64 v[54:55], v[54:55], 0, v[128:129]
	global_store_dwordx4 v[54:55], v[90:93], off
	s_waitcnt lgkmcnt(0)
	v_fma_f32 v50, v60, v109, v50
	v_fma_f32 v51, v61, v109, v51
	v_max_f32_e32 v50, 0, v50
	v_max_f32_e32 v51, 0, v51
	v_fma_f32 v52, v62, v109, v52
	v_fmac_f32_e32 v53, v63, v109
	v_max_f32_e32 v52, 0, v52
	v_max_f32_e32 v53, 0, v53
	v_mul_f32_e32 v50, v50, v50
	v_mul_f32_e32 v51, v51, v51
	v_cvt_pk_bf16_f32 v50, v50, v51
	v_mul_f32_e32 v51, v52, v52
	v_mul_f32_e32 v52, v53, v53
	v_cvt_pk_bf16_f32 v51, v51, v52
	ds_write_b64 v112, v[50:51] offset:48
	ds_read_b128 v[50:53], v130 offset:128
	v_or_b32_e32 v54, v106, v56
	v_ashrrev_i32_e32 v55, 31, v54
	v_lshlrev_b64 v[54:55], 13, v[54:55]
	global_store_dwordx4 v[102:103], v[86:89], off
	s_waitcnt lgkmcnt(0)
	v_fma_f32 v32, v32, v109, v50
	v_fma_f32 v33, v33, v109, v51
	v_max_f32_e32 v32, 0, v32
	v_max_f32_e32 v33, 0, v33
	v_fma_f32 v34, v34, v109, v52
	v_fmac_f32_e32 v53, v35, v109
	v_max_f32_e32 v34, 0, v34
	v_max_f32_e32 v35, 0, v53
	v_mul_f32_e32 v32, v32, v32
	v_mul_f32_e32 v33, v33, v33
	v_cvt_pk_bf16_f32 v32, v32, v33
	v_mul_f32_e32 v33, v34, v34
	v_mul_f32_e32 v34, v35, v35
	v_cvt_pk_bf16_f32 v33, v33, v34
	ds_write_b64 v112, v[32:33] offset:64
	ds_read_b128 v[32:35], v130 offset:160
	v_lshl_add_u64 v[50:51], s[42:43], 0, v[54:55]
	v_lshl_add_u64 v[50:51], v[50:51], 0, v[48:49]
	v_lshl_add_u64 v[50:51], v[50:51], 0, v[128:129]
	global_store_dwordx4 v[50:51], v[78:81], off
	s_waitcnt lgkmcnt(0)
	v_fma_f32 v32, v36, v109, v32
	v_fma_f32 v33, v37, v109, v33
	v_max_f32_e32 v32, 0, v32
	v_max_f32_e32 v33, 0, v33
	v_fma_f32 v34, v38, v109, v34
	v_fmac_f32_e32 v35, v39, v109
	v_max_f32_e32 v34, 0, v34
	v_max_f32_e32 v35, 0, v35
	v_mul_f32_e32 v32, v32, v32
	v_mul_f32_e32 v33, v33, v33
	v_cvt_pk_bf16_f32 v32, v32, v33
	v_mul_f32_e32 v33, v34, v34
	v_mul_f32_e32 v34, v35, v35
	v_cvt_pk_bf16_f32 v33, v33, v34
	ds_write_b64 v112, v[32:33] offset:80
	ds_read_b128 v[32:35], v130 offset:192
	v_or_b32_e32 v38, 12, v107
	v_or_b32_e32 v39, 16, v107
	v_or_b32_e32 v36, v106, v38
	v_ashrrev_i32_e32 v37, 31, v36
	s_waitcnt lgkmcnt(0)
	v_fma_f32 v32, v40, v109, v32
	v_fma_f32 v33, v41, v109, v33
	v_max_f32_e32 v32, 0, v32
	v_max_f32_e32 v33, 0, v33
	v_fma_f32 v34, v42, v109, v34
	v_fmac_f32_e32 v35, v43, v109
	v_max_f32_e32 v34, 0, v34
	v_max_f32_e32 v35, 0, v35
	v_mul_f32_e32 v32, v32, v32
	v_mul_f32_e32 v33, v33, v33
	v_cvt_pk_bf16_f32 v32, v32, v33
	v_mul_f32_e32 v33, v34, v34
	v_mul_f32_e32 v34, v35, v35
	v_cvt_pk_bf16_f32 v33, v33, v34
	ds_write_b64 v112, v[32:33] offset:96
	ds_read_b128 v[32:35], v130 offset:224
	v_lshlrev_b64 v[36:37], 13, v[36:37]
	v_lshl_add_u64 v[36:37], s[42:43], 0, v[36:37]
	v_lshl_add_u64 v[36:37], v[36:37], 0, v[48:49]
	v_lshl_add_u64 v[36:37], v[36:37], 0, v[128:129]
	s_waitcnt lgkmcnt(0)
	v_fma_f32 v32, v44, v109, v32
	v_fma_f32 v33, v45, v109, v33
	v_max_f32_e32 v32, 0, v32
	v_max_f32_e32 v33, 0, v33
	v_fma_f32 v34, v46, v109, v34
	v_fmac_f32_e32 v35, v47, v109
	v_max_f32_e32 v34, 0, v34
	v_max_f32_e32 v35, 0, v35
	v_mul_f32_e32 v32, v32, v32
	v_mul_f32_e32 v33, v33, v33
	v_cvt_pk_bf16_f32 v32, v32, v33
	v_mul_f32_e32 v33, v34, v34
	v_mul_f32_e32 v34, v35, v35
	v_cvt_pk_bf16_f32 v33, v33, v34
	ds_write_b64 v112, v[32:33] offset:112
	ds_read_b128 v[32:35], v130 offset:256
	global_store_dwordx4 v[36:37], v[82:85], off
	v_or_b32_e32 v36, v106, v39
	v_ashrrev_i32_e32 v37, 31, v36
	v_lshlrev_b64 v[36:37], 13, v[36:37]
	s_waitcnt lgkmcnt(0)
	v_fma_f32 v16, v16, v109, v32
	v_fma_f32 v17, v17, v109, v33
	v_max_f32_e32 v16, 0, v16
	v_max_f32_e32 v17, 0, v17
	v_fma_f32 v18, v18, v109, v34
	v_fmac_f32_e32 v35, v19, v109
	v_max_f32_e32 v18, 0, v18
	v_max_f32_e32 v19, 0, v35
	v_mul_f32_e32 v16, v16, v16
	v_mul_f32_e32 v17, v17, v17
	v_cvt_pk_bf16_f32 v16, v16, v17
	v_mul_f32_e32 v17, v18, v18
	v_mul_f32_e32 v18, v19, v19
	v_cvt_pk_bf16_f32 v17, v17, v18
	ds_write_b64 v112, v[16:17] offset:128
	ds_read_b128 v[16:19], v130 offset:288
	v_lshl_add_u64 v[32:33], s[42:43], 0, v[36:37]
	v_lshl_add_u64 v[32:33], v[32:33], 0, v[48:49]
	v_lshl_add_u64 v[32:33], v[32:33], 0, v[128:129]
	global_store_dwordx4 v[32:33], v[98:101], off
	s_waitcnt lgkmcnt(0)
	v_fma_f32 v16, v20, v109, v16
	v_fma_f32 v17, v21, v109, v17
	v_max_f32_e32 v16, 0, v16
	v_max_f32_e32 v17, 0, v17
	v_fma_f32 v18, v22, v109, v18
	v_fmac_f32_e32 v19, v23, v109
	v_max_f32_e32 v18, 0, v18
	v_max_f32_e32 v19, 0, v19
	v_mul_f32_e32 v16, v16, v16
	v_mul_f32_e32 v17, v17, v17
	v_cvt_pk_bf16_f32 v16, v16, v17
	v_mul_f32_e32 v17, v18, v18
	v_mul_f32_e32 v18, v19, v19
	v_cvt_pk_bf16_f32 v17, v17, v18
	ds_write_b64 v112, v[16:17] offset:144
	ds_read_b128 v[16:19], v130 offset:320
	v_or_b32_e32 v22, 20, v107
	v_or_b32_e32 v20, v106, v22
	v_ashrrev_i32_e32 v21, 31, v20
	v_lshlrev_b64 v[20:21], 13, v[20:21]
	s_waitcnt lgkmcnt(0)
	v_fma_f32 v16, v24, v109, v16
	v_fma_f32 v17, v25, v109, v17
	v_max_f32_e32 v16, 0, v16
	v_max_f32_e32 v17, 0, v17
	v_fma_f32 v18, v26, v109, v18
	v_fmac_f32_e32 v19, v27, v109
	v_max_f32_e32 v18, 0, v18
	v_max_f32_e32 v19, 0, v19
	v_mul_f32_e32 v16, v16, v16
	v_mul_f32_e32 v17, v17, v17
	v_cvt_pk_bf16_f32 v16, v16, v17
	v_mul_f32_e32 v17, v18, v18
	v_mul_f32_e32 v18, v19, v19
	v_cvt_pk_bf16_f32 v17, v17, v18
	ds_write_b64 v112, v[16:17] offset:160
	ds_read_b128 v[16:19], v130 offset:352
	v_lshl_add_u64 v[20:21], s[42:43], 0, v[20:21]
	v_lshl_add_u64 v[20:21], v[20:21], 0, v[48:49]
	v_lshl_add_u64 v[20:21], v[20:21], 0, v[128:129]
	v_or_b32_e32 v23, 24, v107
	s_waitcnt lgkmcnt(0)
	v_fma_f32 v16, v28, v109, v16
	v_fma_f32 v17, v29, v109, v17
	v_max_f32_e32 v16, 0, v16
	v_max_f32_e32 v17, 0, v17
	v_fma_f32 v18, v30, v109, v18
	v_fmac_f32_e32 v19, v31, v109
	v_max_f32_e32 v18, 0, v18
	v_max_f32_e32 v19, 0, v19
	v_mul_f32_e32 v16, v16, v16
	v_mul_f32_e32 v17, v17, v17
	v_cvt_pk_bf16_f32 v16, v16, v17
	v_mul_f32_e32 v17, v18, v18
	v_mul_f32_e32 v18, v19, v19
	v_cvt_pk_bf16_f32 v17, v17, v18
	ds_write_b64 v112, v[16:17] offset:176
	ds_read_b128 v[16:19], v130 offset:384
	global_store_dwordx4 v[20:21], v[72:75], off
	v_or_b32_e32 v20, v106, v23
	v_ashrrev_i32_e32 v21, 31, v20
	v_lshlrev_b64 v[20:21], 13, v[20:21]
	s_waitcnt lgkmcnt(0)
	v_fma_f32 v0, v0, v109, v16
	v_fma_f32 v1, v1, v109, v17
	v_max_f32_e32 v0, 0, v0
	v_max_f32_e32 v1, 0, v1
	v_fma_f32 v2, v2, v109, v18
	v_fmac_f32_e32 v19, v3, v109
	v_max_f32_e32 v2, 0, v2
	v_max_f32_e32 v3, 0, v19
	v_mul_f32_e32 v0, v0, v0
	v_mul_f32_e32 v1, v1, v1
	v_cvt_pk_bf16_f32 v0, v0, v1
	v_mul_f32_e32 v1, v2, v2
	v_mul_f32_e32 v2, v3, v3
	v_cvt_pk_bf16_f32 v1, v1, v2
	ds_write_b64 v112, v[0:1] offset:192
	ds_read_b128 v[0:3], v130 offset:416
	v_lshl_add_u64 v[16:17], s[42:43], 0, v[20:21]
	v_lshl_add_u64 v[16:17], v[16:17], 0, v[48:49]
	v_lshl_add_u64 v[16:17], v[16:17], 0, v[128:129]
	global_store_dwordx4 v[16:17], v[68:71], off
	s_waitcnt lgkmcnt(0)
	v_fma_f32 v0, v4, v109, v0
	v_fma_f32 v1, v5, v109, v1
	v_max_f32_e32 v0, 0, v0
	v_max_f32_e32 v1, 0, v1
	v_fma_f32 v2, v6, v109, v2
	v_fmac_f32_e32 v3, v7, v109
	v_max_f32_e32 v2, 0, v2
	v_max_f32_e32 v3, 0, v3
	v_mul_f32_e32 v0, v0, v0
	v_mul_f32_e32 v1, v1, v1
	v_cvt_pk_bf16_f32 v0, v0, v1
	v_mul_f32_e32 v1, v2, v2
	v_mul_f32_e32 v2, v3, v3
	v_cvt_pk_bf16_f32 v1, v1, v2
	ds_write_b64 v112, v[0:1] offset:208
	ds_read_b128 v[0:3], v130 offset:448
	v_or_b32_e32 v16, 28, v107
	v_or_b32_e32 v4, v106, v16
	v_ashrrev_i32_e32 v5, 31, v4
	v_lshlrev_b64 v[4:5], 13, v[4:5]
	s_waitcnt lgkmcnt(0)
	v_fma_f32 v0, v8, v109, v0
	v_fma_f32 v1, v9, v109, v1
	v_max_f32_e32 v0, 0, v0
	v_max_f32_e32 v1, 0, v1
	v_fma_f32 v2, v10, v109, v2
	v_fmac_f32_e32 v3, v11, v109
	v_max_f32_e32 v2, 0, v2
	v_max_f32_e32 v3, 0, v3
	v_mul_f32_e32 v0, v0, v0
	v_mul_f32_e32 v1, v1, v1
	v_cvt_pk_bf16_f32 v0, v0, v1
	v_mul_f32_e32 v1, v2, v2
	v_mul_f32_e32 v2, v3, v3
	v_cvt_pk_bf16_f32 v1, v1, v2
	ds_write_b64 v112, v[0:1] offset:224
	ds_read_b128 v[0:3], v130 offset:480
	v_lshl_add_u64 v[4:5], s[42:43], 0, v[4:5]
	v_lshl_add_u64 v[4:5], v[4:5], 0, v[48:49]
	v_lshl_add_u64 v[4:5], v[4:5], 0, v[128:129]
	v_or_b32_e32 v10, 32, v106
	s_waitcnt lgkmcnt(0)
	v_fma_f32 v0, v12, v109, v0
	v_fma_f32 v1, v13, v109, v1
	v_max_f32_e32 v0, 0, v0
	v_max_f32_e32 v1, 0, v1
	v_fma_f32 v2, v14, v109, v2
	v_fmac_f32_e32 v3, v15, v109
	v_max_f32_e32 v2, 0, v2
	v_max_f32_e32 v3, 0, v3
	v_mul_f32_e32 v0, v0, v0
	v_mul_f32_e32 v1, v1, v1
	v_cvt_pk_bf16_f32 v0, v0, v1
	v_mul_f32_e32 v1, v2, v2
	v_mul_f32_e32 v2, v3, v3
	v_cvt_pk_bf16_f32 v1, v1, v2
	global_store_dwordx4 v[4:5], v[64:67], off
	ds_write_b64 v112, v[0:1] offset:240
	v_or_b32_e32 v4, v10, v107
	ds_read_b128 v[0:3], v108
	v_ashrrev_i32_e32 v5, 31, v4
	v_lshlrev_b64 v[4:5], 13, v[4:5]
	v_lshl_add_u64 v[4:5], s[42:43], 0, v[4:5]
	v_lshl_add_u64 v[4:5], v[4:5], 0, v[48:49]
	v_lshl_add_u64 v[8:9], v[4:5], 0, v[128:129]
	ds_read_b128 v[4:7], v76
	s_waitcnt lgkmcnt(1)
	global_store_dwordx4 v[8:9], v[0:3], off
	s_nop 1
	v_or_b32_e32 v0, v10, v77
	v_ashrrev_i32_e32 v1, 31, v0
	v_lshlrev_b64 v[0:1], 13, v[0:1]
	v_lshl_add_u64 v[0:1], s[42:43], 0, v[0:1]
	v_lshl_add_u64 v[0:1], v[0:1], 0, v[48:49]
	v_lshl_add_u64 v[0:1], v[0:1], 0, v[128:129]
	s_waitcnt lgkmcnt(0)
	global_store_dwordx4 v[0:1], v[4:7], off
	ds_read_b128 v[0:3], v76 offset:1088
	s_nop 0
	v_or_b32_e32 v4, v10, v56
	v_ashrrev_i32_e32 v5, 31, v4
	v_lshlrev_b64 v[4:5], 13, v[4:5]
	v_lshl_add_u64 v[4:5], s[42:43], 0, v[4:5]
	v_lshl_add_u64 v[4:5], v[4:5], 0, v[48:49]
	v_lshl_add_u64 v[8:9], v[4:5], 0, v[128:129]
	ds_read_b128 v[4:7], v76 offset:2176
	s_waitcnt lgkmcnt(1)
	global_store_dwordx4 v[8:9], v[0:3], off
	s_nop 1
	v_or_b32_e32 v0, v10, v38
	v_ashrrev_i32_e32 v1, 31, v0
	v_lshlrev_b64 v[0:1], 13, v[0:1]
	v_lshl_add_u64 v[0:1], s[42:43], 0, v[0:1]
	v_lshl_add_u64 v[0:1], v[0:1], 0, v[48:49]
	v_lshl_add_u64 v[0:1], v[0:1], 0, v[128:129]
	s_waitcnt lgkmcnt(0)
	global_store_dwordx4 v[0:1], v[4:7], off
	ds_read_b128 v[0:3], v76 offset:3264
	s_nop 0
	v_or_b32_e32 v4, v10, v39
	v_ashrrev_i32_e32 v5, 31, v4
	v_lshlrev_b64 v[4:5], 13, v[4:5]
	v_lshl_add_u64 v[4:5], s[42:43], 0, v[4:5]
	v_lshl_add_u64 v[4:5], v[4:5], 0, v[48:49]
	v_lshl_add_u64 v[8:9], v[4:5], 0, v[128:129]
	ds_read_b128 v[4:7], v76 offset:4352
	s_waitcnt lgkmcnt(1)
	global_store_dwordx4 v[8:9], v[0:3], off
	s_nop 1
	v_or_b32_e32 v0, v10, v22
	v_ashrrev_i32_e32 v1, 31, v0
	v_lshlrev_b64 v[0:1], 13, v[0:1]
	v_lshl_add_u64 v[0:1], s[42:43], 0, v[0:1]
	v_lshl_add_u64 v[0:1], v[0:1], 0, v[48:49]
	v_lshl_add_u64 v[0:1], v[0:1], 0, v[128:129]
	s_waitcnt lgkmcnt(0)
	global_store_dwordx4 v[0:1], v[4:7], off
	ds_read_b128 v[0:3], v76 offset:5440
	s_nop 0
	v_or_b32_e32 v4, v10, v23
	v_ashrrev_i32_e32 v5, 31, v4
	v_lshlrev_b64 v[4:5], 13, v[4:5]
	v_lshl_add_u64 v[4:5], s[42:43], 0, v[4:5]
	v_lshl_add_u64 v[4:5], v[4:5], 0, v[48:49]
	v_lshl_add_u64 v[8:9], v[4:5], 0, v[128:129]
	ds_read_b128 v[4:7], v76 offset:6528
	s_waitcnt lgkmcnt(1)
	global_store_dwordx4 v[8:9], v[0:3], off
	s_nop 1
	v_or_b32_e32 v0, v10, v16
	v_ashrrev_i32_e32 v1, 31, v0
	v_lshlrev_b64 v[0:1], 13, v[0:1]
	v_lshl_add_u64 v[0:1], s[42:43], 0, v[0:1]
	v_lshl_add_u64 v[0:1], v[0:1], 0, v[48:49]
	v_lshl_add_u64 v[0:1], v[0:1], 0, v[128:129]
	s_waitcnt lgkmcnt(0)
	global_store_dwordx4 v[0:1], v[4:7], off
	s_cbranch_scc0 .LBB0_1370
